# GEMM phase prologues de-serialised: second batch of prologue tile DMAs issued behind the first (one memory round trip per phase start instead of two)
# speedup vs baseline: 1.0030x; 1.0030x over previous
; #define PG8_STAGE(bufoff, gbase) do { _Pragma("unroll") for (int _i = 0; _i < 2; ++_i) \
;         __builtin_amdgcn_global_load_lds((const unsigned*)((const char*)(gbase) + voffA[_i]), (LAS unsigned*)(lds + (bufoff) + ldsw + _i * 8192), 16, 0, 0); } while (0)
; #define PG8_WAIT_V(n) asm volatile("s_waitcnt vmcnt(" #n ")" ::: "memory")
; #define PG8_BAR __builtin_amdgcn_s_barrier()
; template <class Epi, bool ALIGN_EPI, bool SP2, bool BF = false, bool HALFM = false, class Order = StaticOrder>
; __device__ __forceinline__ void gemm_phase(LAS unsigned char* lds, const int tid, const Gemm g, const Order& S, const Epi& E, const bool dry = false) {
;     ...
;     if constexpr (SP2) {
;         PG8_STAGE(PG8_SB(0, 0), cB); PG8_STAGE(PG8_SB(0, 1), cB + hstep); PG8_STAGE(PG8_SA(0, 0), cA); PG8_STAGE(PG8_SA(0, 1), cA + hstep);
;         if (wr == 1) PG8_BAR;
;         PG8_WAIT_V(2); PG8_BAR;
;         PG8_STAGE(PG8_SB(1, 0), cB + kstep); PG8_STAGE(PG8_SA(1, 0), cA + kstep); PG8_STAGE(PG8_SB(1, 1), cB + hstep + kstep);
;         PG8_WAIT_V(6); PG8_BAR;
.LBB0_446:
	s_add_i32 s85, s74, 0x18000
	s_add_i32 s86, s85, s7
	s_and_b32 s83, s9, 3
	s_lshl_b32 s84, s8, 6
	s_lshl_b32 s1, s8, 13
	v_lshl_add_u64 v[8:9], v[8:9], 0, s[94:95]
	s_mov_b32 m0, s86
	s_add_i32 s87, s86, 0x2000
	s_add_i32 s76, s79, 0x8000
	s_add_i32 s48, s79, 0xa000
	global_load_lds_dwordx4 v[8:9], off
	v_lshl_add_u64 v[6:7], v[6:7], 0, s[94:95]
	s_mov_b32 m0, s87
	s_add_u32 s12, s38, 0x40080
	global_load_lds_dwordx4 v[6:7], off
	v_lshl_add_u64 v[2:3], v[2:3], 0, s[94:95]
	s_mov_b32 m0, s76
	s_addc_u32 s13, s39, 0
	s_add_i32 s51, s74, 0x1c000
	global_load_lds_dwordx4 v[2:3], off
	v_lshl_add_u64 v[2:3], v[4:5], 0, s[94:95]
	s_mov_b32 m0, s48
	s_add_i32 s8, s51, s7
	global_load_lds_dwordx4 v[2:3], off
	v_lshl_add_u64 v[2:3], s[12:13], 0, v[164:165]
	s_mov_b32 m0, s8
	s_add_i32 s9, s8, 0x2000
	global_load_lds_dwordx4 v[2:3], off
	v_lshl_add_u64 v[2:3], s[12:13], 0, v[166:167]
	s_mov_b32 m0, s9
	v_lshlrev_b32_e32 v10, 2, v131
	global_load_lds_dwordx4 v[2:3], off
	s_waitcnt vmcnt(8)
	s_barrier
	v_lshlrev_b32_e32 v2, 14, v181
	v_and_b32_e32 v2, 0xffff8000, v2
	v_lshl_add_u32 v2, v183, 11, v2
	v_and_b32_e32 v3, 1, v181
	v_lshl_or_b32 v2, v3, 6, v2
	v_lshl_add_u32 v168, v184, 1, v2
	v_lshlrev_b32_e32 v2, 14, v182
	v_lshl_or_b32 v0, v131, 6, v187
	v_and_b32_e32 v10, 32, v10
	s_cmpk_lt_u32 s6, 0x100
	v_and_b32_e32 v2, 0xffff8000, v2
	v_bitop3_b32 v0, v0, s1, v10 bitop3:0xde
	s_waitcnt vmcnt(6)
	s_cselect_b64 s[14:15], -1, 0
	s_lshl_b32 s29, s83, 6
	s_ashr_i32 s6, s73, 31
	s_ashr_i32 s11, s10, 31
	s_lshr_b32 s1, s47, 1
	v_lshl_add_u32 v2, v185, 11, v2
	v_and_b32_e32 v3, 1, v182
	s_cmp_lg_u32 s41, 0
	v_lshl_or_b32 v2, v3, 6, v2
	v_lshl_or_b32 v189, s83, 12, v188
	v_writelane_b32 v253, s1, 7
	s_mov_b32 s12, 0
	s_cselect_b64 s[16:17], -1, 0
	s_or_b32 s13, s41, 16
	s_or_b32 s7, s41, 0x80
	s_or_b32 s96, s41, 0x90
	v_mov_b32_e32 v169, v1
	v_lshl_add_u32 v170, v186, 1, v2
	v_mov_b32_e32 v171, v1
	v_add_u32_e32 v190, s74, v0
	s_barrier
	s_branch .LBB0_449

; #define PG8_STAGE(bufoff, gbase) do { _Pragma("unroll") for (int _i = 0; _i < 2; ++_i) \
;         __builtin_amdgcn_global_load_lds((const unsigned*)((const char*)(gbase) + voffA[_i]), (LAS unsigned*)(lds + (bufoff) + ldsw + _i * 8192), 16, 0, 0); } while (0)
; #define PG8_WAIT_V(n) asm volatile("s_waitcnt vmcnt(" #n ")" ::: "memory")
; #define PG8_BAR __builtin_amdgcn_s_barrier()
; template <class Epi, bool ALIGN_EPI, bool SP2, bool BF = false, bool HALFM = false, class Order = StaticOrder>
; __device__ __forceinline__ void gemm_phase(LAS unsigned char* lds, const int tid, const Gemm g, const Order& S, const Epi& E, const bool dry = false) {
;     ...
;     f32x4 acc[2][2][4][2];
; #pragma unroll
;     for (int a = 0; a < 2; ++a)
; #pragma unroll
;         for (int b = 0; b < 2; ++b)
; #pragma unroll
;             for (int m = 0; m < 4; ++m)
; #pragma unroll
;                 for (int n = 0; n < 2; ++n) acc[a][b][m][n] = (f32x4){0.f, 0.f, 0.f, 0.f};
;     h16x8 At[4][2], B0[2][2], B1[2][2];
;     const char* cA = (const char*)g.A + (size_t)cur.pm * tstep + (HALFM ? (size_t)cur.hm * hstep : (size_t)0); const char* cB = (const char*)g.Bt + (size_t)cur.pn * tstep;
;     if constexpr (SP2) {
;         PG8_STAGE(PG8_SB(0, 0), cB); PG8_STAGE(PG8_SB(0, 1), cB + hstep); PG8_STAGE(PG8_SA(0, 0), cA); PG8_STAGE(PG8_SA(0, 1), cA + hstep);
;         if (wr == 1) PG8_BAR;
;         PG8_WAIT_V(2); PG8_BAR;
;         PG8_STAGE(PG8_SB(1, 0), cB + kstep); PG8_STAGE(PG8_SA(1, 0), cA + kstep); PG8_STAGE(PG8_SB(1, 1), cB + hstep + kstep);
;         PG8_WAIT_V(6); PG8_BAR;
.LBB0_503:
	v_lshlrev_b32_e32 v10, 2, v131
	s_lshl_b32 s1, s29, 6
	v_lshl_or_b32 v0, v131, 6, v187
	s_lshl_b32 s29, s29, 13
	v_and_b32_e32 v10, 32, v10
	v_bitop3_b32 v11, v0, s29, v10 bitop3:0xde
	s_add_i32 s29, s74, 0x18000
	s_and_b32 s5, s36, 3
	s_add_i32 s36, s29, s6
	v_lshl_add_u64 v[8:9], v[8:9], 0, s[94:95]
	s_mov_b32 m0, s36
	s_add_i32 s37, s36, 0x2000
	s_add_i32 s38, s22, 0x8000
	s_add_i32 s39, s22, 0xa000
	global_load_lds_dwordx4 v[8:9], off
	v_lshl_add_u64 v[6:7], v[6:7], 0, s[94:95]
	s_mov_b32 m0, s37
	s_add_u32 s44, s2, 0x40080
	global_load_lds_dwordx4 v[6:7], off
	v_lshl_add_u64 v[4:5], v[4:5], 0, s[94:95]
	s_mov_b32 m0, s38
	s_addc_u32 s45, s3, 0
	s_add_i32 s42, s74, 0x1c000
	global_load_lds_dwordx4 v[4:5], off
	v_lshl_add_u64 v[2:3], v[2:3], 0, s[94:95]
	s_mov_b32 m0, s39
	s_add_i32 s43, s42, s6
	global_load_lds_dwordx4 v[2:3], off
	v_lshl_add_u64 v[2:3], s[44:45], 0, v[164:165]
	s_mov_b32 m0, s43
	v_readlane_b32 s56, v251, 0
	global_load_lds_dwordx4 v[2:3], off
	v_lshl_add_u64 v[2:3], s[44:45], 0, v[166:167]
	s_add_i32 s44, s43, 0x2000
	s_mov_b32 m0, s44
	s_add_u32 s6, s12, s7
	global_load_lds_dwordx4 v[2:3], off
	s_waitcnt vmcnt(8)
	s_barrier
	v_readlane_b32 s57, v251, 1
	s_addc_u32 s7, s13, 0
	v_readlane_b32 s58, v251, 2
	v_readlane_b32 s59, v251, 3
	s_mov_b64 s[48:49], s[56:57]
	v_lshlrev_b32_e32 v0, 14, v181
	s_add_u32 s45, s48, s6
	v_and_b32_e32 v0, 0xffff8000, v0
	s_addc_u32 s47, s49, s7
	v_lshl_add_u32 v0, v183, 11, v0
	v_and_b32_e32 v2, 1, v181
	v_readlane_b32 s12, v252, 20
	v_lshl_or_b32 v0, v2, 6, v0
	s_add_u32 s6, s12, s6
	v_readlane_b32 s12, v252, 21
	v_lshl_add_u32 v0, v184, 1, v0
	s_addc_u32 s7, s12, s7
	v_lshl_add_u64 v[2:3], s[6:7], 0, v[0:1]
	v_lshlrev_b32_e32 v0, 14, v182
	v_and_b32_e32 v0, 0xffff8000, v0
	v_lshl_add_u32 v0, v185, 11, v0
	v_and_b32_e32 v4, 1, v182
	v_lshl_or_b32 v0, v4, 6, v0
	v_lshl_add_u32 v0, v186, 1, v0
	v_lshl_add_u64 v[4:5], s[6:7], 0, v[0:1]
	s_add_u32 s6, s54, s10
	s_addc_u32 s7, s55, s11
	v_readlane_b32 s10, v253, 0
	v_readlane_b32 s11, v253, 1
	s_add_u32 s6, s10, s6
	s_waitcnt vmcnt(6)
	s_addc_u32 s7, s11, s7
	s_mov_b64 s[50:51], s[58:59]
	s_add_u32 s48, s6, 0x1d00100
	v_mov_b32_e32 v18, 0
	v_lshl_or_b32 v10, s5, 12, v188
	s_addc_u32 s49, s7, 0
	s_mov_b32 s50, -2
	s_mov_b64 s[6:7], 0
	v_add_u32_e32 v0, s74, v11
	v_mov_b32_e32 v19, v18
	v_mov_b32_e32 v20, v18
	v_mov_b32_e32 v21, v18
	s_waitcnt vmcnt(0)
	v_mov_b32_e32 v22, v18
	v_mov_b32_e32 v23, v18
	v_mov_b32_e32 v24, v18
	v_mov_b32_e32 v25, v18
	v_mov_b32_e32 v50, v18
	v_mov_b32_e32 v51, v18
	v_mov_b32_e32 v52, v18
	v_mov_b32_e32 v53, v18
	v_mov_b32_e32 v54, v18
	v_mov_b32_e32 v55, v18
	v_mov_b32_e32 v56, v18
	v_mov_b32_e32 v57, v18
	v_mov_b32_e32 v66, v18
	v_mov_b32_e32 v67, v18
	v_mov_b32_e32 v68, v18
	v_mov_b32_e32 v69, v18
	v_mov_b32_e32 v70, v18
	v_mov_b32_e32 v71, v18
	v_mov_b32_e32 v72, v18
	v_mov_b32_e32 v73, v18
	v_mov_b32_e32 v82, v18
	v_mov_b32_e32 v83, v18
	v_mov_b32_e32 v84, v18
	v_mov_b32_e32 v85, v18
	v_mov_b32_e32 v86, v18
	v_mov_b32_e32 v87, v18
	v_mov_b32_e32 v88, v18
	v_mov_b32_e32 v89, v18
	v_mov_b32_e32 v26, v18
	v_mov_b32_e32 v27, v18
	v_mov_b32_e32 v28, v18
	v_mov_b32_e32 v29, v18
	v_mov_b32_e32 v30, v18
	v_mov_b32_e32 v31, v18
	v_mov_b32_e32 v32, v18
	v_mov_b32_e32 v33, v18
	v_mov_b32_e32 v58, v18
	v_mov_b32_e32 v59, v18
	v_mov_b32_e32 v60, v18
	v_mov_b32_e32 v61, v18
	v_mov_b32_e32 v62, v18
	v_mov_b32_e32 v63, v18
	v_mov_b32_e32 v64, v18
	v_mov_b32_e32 v65, v18
	v_mov_b32_e32 v74, v18
	v_mov_b32_e32 v75, v18
	v_mov_b32_e32 v76, v18
	v_mov_b32_e32 v77, v18
	v_mov_b32_e32 v78, v18
	v_mov_b32_e32 v79, v18
	v_mov_b32_e32 v80, v18
	v_mov_b32_e32 v81, v18
	v_mov_b32_e32 v90, v18
	v_mov_b32_e32 v91, v18
	v_mov_b32_e32 v92, v18
	v_mov_b32_e32 v93, v18
	v_mov_b32_e32 v94, v18
	v_mov_b32_e32 v95, v18
	v_mov_b32_e32 v96, v18
	v_mov_b32_e32 v97, v18
	s_barrier
	v_readlane_b32 s60, v251, 4
	v_readlane_b32 s61, v251, 5
	v_readlane_b32 s62, v251, 6
	v_readlane_b32 s63, v251, 7

; #define LAS __attribute__((address_space(3)))
; #define PG8_STAGE(bufoff, gbase) do { _Pragma("unroll") for (int _i = 0; _i < 2; ++_i) \
;         __builtin_amdgcn_global_load_lds((const unsigned*)((const char*)(gbase) + voffA[_i]), (LAS unsigned*)(lds + (bufoff) + ldsw + _i * 8192), 16, 0, 0); } while (0)
; #define PG8_WAIT_V(n) asm volatile("s_waitcnt vmcnt(" #n ")" ::: "memory")
; #define PG8_BAR __builtin_amdgcn_s_barrier()
; template <class Epi, bool ALIGN_EPI, bool SP2, bool BF = false, bool HALFM = false, class Order = StaticOrder>
; __device__ __forceinline__ void gemm_phase(LAS unsigned char* lds, const int tid, const Gemm g, const Order& S, const Epi& E, const bool dry = false) {
;     ...
;     if constexpr (SP2) {
;         PG8_STAGE(PG8_SB(0, 0), cB); PG8_STAGE(PG8_SB(0, 1), cB + hstep); PG8_STAGE(PG8_SA(0, 0), cA); PG8_STAGE(PG8_SA(0, 1), cA + hstep);
;         if (wr == 1) PG8_BAR;
;         PG8_WAIT_V(2); PG8_BAR;
;         PG8_STAGE(PG8_SB(1, 0), cB + kstep); PG8_STAGE(PG8_SA(1, 0), cA + kstep); PG8_STAGE(PG8_SB(1, 1), cB + hstep + kstep);
;         PG8_WAIT_V(6); PG8_BAR;
; __device__ __forceinline__ void ph_inproj(Frame& F, int l, bool dry, bool nost) {
;     ...
;     EpiIn E{(unsigned)(WS_SHW + (size_t)l * 17 * NPAD * 4), F.p.gq + l * 64, F.p.gk + l * 64, F.p.bgates + l * 16, ws, nost ? nullptr : ws, (const LAS float*)(F.lds + ROPE_LDS_OFF)};
;     ...
;     if (dry) pg8::gemm_phase<EpiIn, true, true, true>(F.lds, F.tid, g, S, E, dry); else
;     ...
;     pg8::gemm_phase<EpiIn, true, true>(F.lds, F.tid, g, S, E, dry);
.LBB0_555:
	s_lshl_b32 s12, s66, 4
	s_mul_i32 s3, s66, 0x3b800
	s_lshl_b32 s0, s66, 6
	s_ashr_i32 s13, s12, 31
	v_readlane_b32 s56, v252, 28
	s_ashr_i32 s1, s0, 31
	s_lshl_b64 s[12:13], s[12:13], 2
	v_readlane_b32 s64, v252, 36
	v_bfe_u32 v197, v246, 4, 2
	v_readlane_b32 s65, v252, 37
	s_add_u32 s12, s64, s12
	v_and_b32_e32 v196, 15, v246
	v_lshlrev_b32_e32 v16, 4, v197
	v_lshlrev_b32_e32 v17, 2, v246
	s_addc_u32 s13, s65, s13
	s_and_b32 s76, s10, 3
	v_lshl_or_b32 v16, v196, 6, v16
	s_lshl_b32 s5, s11, 13
	v_and_b32_e32 v17, 32, v17
	s_add_i32 s79, s74, 0x18000
	v_bitop3_b32 v18, v16, s5, v17 bitop3:0xde
	s_lshl_b32 s5, s76, 12
	s_add_i32 s80, s79, s9
	s_lshl_b32 s77, s11, 6
	v_bitop3_b32 v198, s5, v16, v17 bitop3:0xf6
	s_add_i32 s5, s74, 0x20400
	v_lshl_add_u64 v[8:9], v[8:9], 0, s[94:95]
	s_mov_b32 m0, s80
	s_add_i32 s81, s80, 0x2000
	s_add_i32 s82, s52, 0x8000
	s_add_i32 s83, s52, 0xa000
	global_load_lds_dwordx4 v[8:9], off
	v_lshl_add_u64 v[6:7], v[6:7], 0, s[94:95]
	s_mov_b32 m0, s81
	s_add_u32 s10, s36, 0x40080
	global_load_lds_dwordx4 v[6:7], off
	v_lshl_add_u64 v[2:3], v[2:3], 0, s[94:95]
	s_mov_b32 m0, s82
	s_addc_u32 s11, s37, 0
	s_add_i32 s84, s74, 0x1c000
	global_load_lds_dwordx4 v[2:3], off
	v_lshl_add_u64 v[2:3], v[4:5], 0, s[94:95]
	s_mov_b32 m0, s83
	s_add_i32 s85, s84, s9
	global_load_lds_dwordx4 v[2:3], off
	v_lshl_add_u64 v[2:3], s[10:11], 0, v[0:1]
	s_mov_b32 m0, s85
	s_add_i32 s86, s85, 0x2000
	global_load_lds_dwordx4 v[2:3], off
	v_lshl_add_u64 v[2:3], s[10:11], 0, v[164:165]
	s_mov_b32 m0, s86
	v_writelane_b32 v253, s12, 5
	global_load_lds_dwordx4 v[2:3], off
	s_waitcnt vmcnt(8)
	s_barrier
	v_lshlrev_b32_e32 v2, 14, v13
	v_and_b32_e32 v2, 0xffff8000, v2
	v_writelane_b32 v253, s13, 6
	v_lshl_add_u32 v2, v14, 11, v2
	v_and_b32_e32 v3, 1, v13
	v_writelane_b32 v253, s5, 7
	v_lshl_or_b32 v2, v3, 6, v2
	s_cmpk_lt_u32 s8, 0x100
	v_readlane_b32 s8, v253, 0
	v_lshl_add_u32 v166, v15, 1, v2
	v_lshlrev_b32_e32 v2, 14, v10
	s_cselect_b64 s[12:13], -1, 0
	s_lshl_b32 s5, s76, 7
	s_ashr_i32 s87, s73, 31
	v_readlane_b32 s9, v253, 1
	v_and_b32_e32 v2, 0xffff8000, v2
	v_readlane_b32 s70, v252, 42
	v_readlane_b32 s71, v252, 43
	s_waitcnt vmcnt(6)
	s_cmp_eq_u64 s[8:9], 0
	v_lshl_add_u32 v2, v11, 11, v2
	v_and_b32_e32 v3, 1, v10
	s_cselect_b64 s[14:15], -1, 0
	s_or_b32 s96, s3, s5
	s_add_i32 s3, s74, 0x21400
	v_lshl_or_b32 v2, v3, 6, v2
	v_readlane_b32 s70, v252, 58
	s_add_i32 s96, s96, 0x2680000
	v_writelane_b32 v253, s3, 8
	v_mov_b32_e32 v167, v1
	v_lshl_add_u32 v168, v12, 1, v2
	v_mov_b32_e32 v169, v1
	s_mov_b32 s10, 0
	v_add_u32_e32 v199, s74, v18
	s_lshl_b64 s[16:17], s[0:1], 2
	v_readlane_b32 s71, v252, 59
	v_readlane_b32 s57, v252, 29
	v_readlane_b32 s58, v252, 30
	v_readlane_b32 s59, v252, 31
	v_readlane_b32 s60, v252, 32
	v_readlane_b32 s61, v252, 33
	v_readlane_b32 s62, v252, 34
	v_readlane_b32 s63, v252, 35
	v_readlane_b32 s66, v252, 38
	v_readlane_b32 s67, v252, 39
	v_readlane_b32 s68, v252, 40
	v_readlane_b32 s69, v252, 41
	s_barrier
	s_mov_b32 s100, 0
	s_branch .LBB0_558
